# speedup vs baseline: 1.0095x; 1.0095x over previous
; #define SBAR() __builtin_amdgcn_sched_barrier(0)
; #define QKT(P0, P1, KP) do { if constexpr (FIXED) qkt8(P0, P1, KP, q8, r32, hi); else qkt<false>(P0, P1, (const bf16_t*)(KP), qr, r32, hi, qinit); } while (0)
; template <bool FIXED> ...
;     ...
;     int bp = 0, bc = 1, bn = 2;
;     for (int j = 1; j + 1 < NT; j += 2) {
;         SBAR(); QKT(pB0, pB1, (const char*)K_lds + bc * SHM_K);
.LBB0_1027:
	v_readfirstlane_b32 s50, v195
	s_nop 3
	s_cmp_lt_u32 s50, 0x100
	s_cbranch_scc1 .Lprio_done
	s_setprio 1

; __device__ __forceinline__ void qkt8(f32x16& p0, f32x16& p1, const char* Ks, const i32x8* q8, int r32, int hi) {
;     const int s127 = 127, s124 = 124;
;     const int sw0 = (r32 >> 1) & 7, sw1 = ((32 + r32) >> 1) & 7; const char* rp0 = Ks + r32 * 128; const char* rp1 = Ks + (32 + r32) * 128;
;     ...
;     {   i32x8 ka = K8LD(rp0, 0, sw0), kb = K8LD(rp1, 0, sw1);
;         asm volatile("s_waitcnt lgkmcnt(0)" ::: "memory");
;         asm volatile("v_mfma_scale_f32_32x32x64_f8f6f4 %0, %1, %2, -4.0, %3, %4 op_sel_hi:[0,0,0]" : "=&v"(p0) : "v"(ka), "v"(q8[0]), "v"(s127), "v"(s124));
;         asm volatile("v_mfma_scale_f32_32x32x64_f8f6f4 %0, %1, %2, -4.0, %3, %4 op_sel_hi:[0,0,0]" : "=&v"(p1) : "v"(kb), "v"(q8[0]), "v"(s127), "v"(s124)); }
;     {   i32x8 ka = K8LD(rp0, 1, sw0), kb = K8LD(rp1, 1, sw1);
;         asm volatile("s_waitcnt lgkmcnt(0)" ::: "memory");
;         asm volatile("v_mfma_scale_f32_32x32x64_f8f6f4 %0, %1, %2, %0, %3, %4 op_sel_hi:[0,0,0]" : "+v"(p0) : "v"(ka), "v"(q8[1]), "v"(s127), "v"(s124));
;         asm volatile("v_mfma_scale_f32_32x32x64_f8f6f4 %0, %1, %2, %0, %3, %4 op_sel_hi:[0,0,0]" : "+v"(p1) : "v"(kb), "v"(q8[1]), "v"(s127), "v"(s124)); }
; }
; __device__ __forceinline__ void finishSM8(f32x16& p0, f32x16& p1, float& l_reg, i32x8& pa) {
;     for (int r = 0; r < 16; ++r) p1[r] = __builtin_amdgcn_exp2f(p1[r]);
;     float ps = 0; for (int r = 0; r < 16; ++r) ps += p0[r]; for (int r = 0; r < 16; ++r) ps += p1[r];
;     l_reg += ps;
; #pragma unroll
;     for (int q = 0; q < 4; ++q) { int v = 0; v = __builtin_amdgcn_cvt_pk_bf8_f32(p0[4 * q], p0[4 * q + 1], v, false); v = __builtin_amdgcn_cvt_pk_bf8_f32(p0[4 * q + 2], p0[4 * q + 3], v, true); pa[q] = v; }
; #pragma unroll
;     for (int q = 0; q < 4; ++q) { int v = 0; v = __builtin_amdgcn_cvt_pk_bf8_f32(p1[4 * q], p1[4 * q + 1], v, false); v = __builtin_amdgcn_cvt_pk_bf8_f32(p1[4 * q + 2], p1[4 * q + 3], v, true); pa[4 + q] = v; }
; }
; template <bool EXPQ>
; __device__ __forceinline__ void pv8(f32x16* o, const char* Vs, const i32x8& pa, int r32, int hi, f32x16& pe) {
;     const int s127 = 127; const char* vp = Vs + r32 * 80 + hi * 32;
;     {   const i32x8 v0 = *(const i32x8*)(vp), v1 = *(const i32x8*)(vp + 32 * 80);
;         asm volatile("s_waitcnt lgkmcnt(0)" ::: "memory");
.LBB0_1031:
	s_setprio 0
	v_and_b32_e32 v96, 0x3fffffc0, v195
	v_lshl_add_u32 v128, v96, 2, s64
	v_add_u32_e32 v129, s49, v201
	v_add_u32_e32 v100, v129, v202
	v_add_u32_e32 v104, v129, v203
	ds_read_b128 v[96:99], v100 offset:49152
	ds_read_b128 v[130:133], v100 offset:53248
	ds_read_b128 v[100:103], v104 offset:49152
	ds_read_b128 v[134:137], v104 offset:53248
	s_waitcnt lgkmcnt(0)
	s_waitcnt lgkmcnt(1)
	v_mfma_scale_f32_32x32x64_f8f6f4 v[112:127], v[96:103], v[152:159], -4.0, v189, v190 op_sel_hi:[0,0,0]
	s_waitcnt lgkmcnt(0)
	v_mfma_scale_f32_32x32x64_f8f6f4 v[96:111], v[130:137], v[152:159], -4.0, v189, v190 op_sel_hi:[0,0,0]
	v_add_u32_e32 v134, v129, v205
	v_add_u32_e32 v129, v129, v206
	ds_read_b128 v[130:133], v134 offset:49152
	ds_read_b128 v[152:155], v134 offset:53248
	ds_read_b128 v[134:137], v129 offset:49152
	ds_read_b128 v[156:159], v129 offset:53248
	v_exp_f32_e32 v129, v80
	v_add_f32_e32 v80, 0, v64
	v_add_f32_e32 v80, v65, v80
	v_add_f32_e32 v80, v66, v80
	v_add_f32_e32 v80, v67, v80
	v_add_f32_e32 v80, v68, v80
	v_add_f32_e32 v80, v69, v80
	v_add_f32_e32 v80, v70, v80
	v_add_f32_e32 v80, v71, v80
	v_add_f32_e32 v80, v72, v80
	v_add_f32_e32 v80, v73, v80
	v_add_f32_e32 v80, v74, v80
	v_add_f32_e32 v80, v75, v80
	v_add_f32_e32 v80, v76, v80
	s_waitcnt lgkmcnt(0)
	s_waitcnt lgkmcnt(1)
	v_mfma_scale_f32_32x32x64_f8f6f4 v[112:127], v[130:137], v[144:151], v[112:127], v189, v190 op_sel_hi:[0,0,0]
	v_exp_f32_e32 v130, v81
	v_add_f32_e32 v80, v77, v80
	v_exp_f32_e32 v131, v82
	v_add_f32_e32 v80, v78, v80
	v_exp_f32_e32 v132, v83
	v_add_f32_e32 v80, v79, v80
	v_exp_f32_e32 v133, v84
	v_add_f32_e32 v80, v129, v80
	v_exp_f32_e32 v134, v85
	v_add_f32_e32 v80, v130, v80
	v_exp_f32_e32 v135, v86
	v_add_f32_e32 v80, v131, v80
	v_exp_f32_e32 v136, v87
	v_add_f32_e32 v80, v132, v80
	v_exp_f32_e32 v87, v88
	v_add_f32_e32 v80, v133, v80
	v_exp_f32_e32 v88, v89
	v_add_f32_e32 v80, v134, v80
	v_exp_f32_e32 v89, v90
	v_add_f32_e32 v80, v135, v80
	v_exp_f32_e32 v90, v91
	v_add_f32_e32 v80, v136, v80
	v_exp_f32_e32 v91, v92
	v_add_f32_e32 v80, v87, v80
	v_exp_f32_e32 v92, v93
	v_add_f32_e32 v80, v88, v80
	v_add_f32_e32 v80, v89, v80
	v_add_f32_e32 v80, v90, v80
	v_exp_f32_e32 v93, v94
	v_add_f32_e32 v80, v91, v80
	v_mov_b32_e32 v86, v179
	v_exp_f32_e32 v94, v95
	v_add_f32_e32 v95, v92, v80
	v_mov_b32_e32 v80, v179
	v_mov_b32_e32 v81, v179
	v_mov_b32_e32 v82, v179
	v_mov_b32_e32 v83, v179
	v_mov_b32_e32 v84, v179
	v_mov_b32_e32 v85, v179
	v_cvt_pk_bf8_f32 v86, v87, v88
	v_mov_b32_e32 v87, v179
	v_cvt_pk_bf8_f32 v80, v64, v65
	v_cvt_pk_bf8_f32 v81, v68, v69
	v_cvt_pk_bf8_f32 v82, v72, v73
	v_cvt_pk_bf8_f32 v83, v76, v77
	v_cvt_pk_bf8_f32 v84, v129, v130
	v_cvt_pk_bf8_f32 v85, v133, v134
	v_cvt_pk_bf8_f32 v87, v91, v92
	v_add_f32_e32 v64, v93, v95
	v_add_f32_e32 v64, v94, v64
	s_waitcnt lgkmcnt(0)
	v_mfma_scale_f32_32x32x64_f8f6f4 v[96:111], v[152:159], v[144:151], v[96:111], v189, v190 op_sel_hi:[0,0,0]
	v_cvt_pk_bf8_f32 v80, v66, v67 op_sel:[0,0,1]
	v_cvt_pk_bf8_f32 v81, v70, v71 op_sel:[0,0,1]
	v_cvt_pk_bf8_f32 v82, v74, v75 op_sel:[0,0,1]
	v_cvt_pk_bf8_f32 v83, v78, v79 op_sel:[0,0,1]
	v_cvt_pk_bf8_f32 v84, v131, v132 op_sel:[0,0,1]
	v_cvt_pk_bf8_f32 v85, v135, v136 op_sel:[0,0,1]
	v_cvt_pk_bf8_f32 v86, v89, v90 op_sel:[0,0,1]
	v_cvt_pk_bf8_f32 v87, v93, v94 op_sel:[0,0,1]
	v_add_f32_e32 v129, v178, v64
	v_add3_u32 v130, s48, v197, v193
	ds_read_b128 v[64:67], v130
	ds_read_b128 v[68:71], v130 offset:16
	ds_read_b128 v[76:79], v130 offset:2576
	ds_read_b128 v[72:75], v130 offset:2560
	s_waitcnt lgkmcnt(0)
	s_waitcnt lgkmcnt(2)
	v_mfma_scale_f32_32x32x64_f8f6f4 v[0:15], v[80:87], v[64:71], v[0:15], v189, v189 op_sel_hi:[0,0,0] cbsz:1
	v_exp_f32_e32 v64, v112
	s_waitcnt lgkmcnt(0)
; __device__ __forceinline__ void finishSM8(f32x16& p0, f32x16& p1, float& l_reg, i32x8& pa) {
;     for (int r = 0; r < 16; ++r) p1[r] = __builtin_amdgcn_exp2f(p1[r]);
;     float ps = 0; for (int r = 0; r < 16; ++r) ps += p0[r]; for (int r = 0; r < 16; ++r) ps += p1[r];
;     l_reg += ps;
; #pragma unroll
;     for (int q = 0; q < 4; ++q) { int v = 0; v = __builtin_amdgcn_cvt_pk_bf8_f32(p0[4 * q], p0[4 * q + 1], v, false); v = __builtin_amdgcn_cvt_pk_bf8_f32(p0[4 * q + 2], p0[4 * q + 3], v, true); pa[q] = v; }
; #pragma unroll
;     for (int q = 0; q < 4; ++q) { int v = 0; v = __builtin_amdgcn_cvt_pk_bf8_f32(p1[4 * q], p1[4 * q + 1], v, false); v = __builtin_amdgcn_cvt_pk_bf8_f32(p1[4 * q + 2], p1[4 * q + 3], v, true); pa[4 + q] = v; }
; }
; template <bool EXPQ>
; __device__ __forceinline__ void pv8(f32x16* o, const char* Vs, const i32x8& pa, int r32, int hi, f32x16& pe) {
;     const int s127 = 127; const char* vp = Vs + r32 * 80 + hi * 32;
;     {   const i32x8 v0 = *(const i32x8*)(vp), v1 = *(const i32x8*)(vp + 32 * 80);
;         asm volatile("s_waitcnt lgkmcnt(0)" ::: "memory");
;         asm volatile("v_mfma_scale_f32_32x32x64_f8f6f4 %0, %1, %2, %0, %3, %3 op_sel_hi:[0,0,0] cbsz:1" : "+v"(o[0]) : "v"(pa), "v"(v0), "v"(s127));
;         asm volatile("v_mfma_scale_f32_32x32x64_f8f6f4 %0, %1, %2, %0, %3, %3 op_sel_hi:[0,0,0] cbsz:1" : "+v"(o[1]) : "v"(pa), "v"(v1), "v"(s127)); }
;     {   const i32x8 v2 = *(const i32x8*)(vp + 64 * 80), v3 = *(const i32x8*)(vp + 96 * 80);
;         if constexpr (EXPQ) { for (int r = 0; r < 16; ++r) pe[r] = __builtin_amdgcn_exp2f(pe[r]); asm volatile("" : "+v"(pe)); }
;         asm volatile("s_waitcnt lgkmcnt(0)" ::: "memory");
;         asm volatile("v_mfma_scale_f32_32x32x64_f8f6f4 %0, %1, %2, %0, %3, %3 op_sel_hi:[0,0,0] cbsz:1" : "+v"(o[2]) : "v"(pa), "v"(v2), "v"(s127));
;         asm volatile("v_mfma_scale_f32_32x32x64_f8f6f4 %0, %1, %2, %0, %3, %3 op_sel_hi:[0,0,0] cbsz:1" : "+v"(o[3]) : "v"(pa), "v"(v3), "v"(s127)); }
; }
; template <bool FIXED> ...
;     ...
;     if constexpr (FIXED) { asm volatile("s_nop 15\n s_nop 15\n s_nop 15\n s_nop 15\n s_nop 15" : "+v"(o[0]), "+v"(o[1]), "+v"(o[2]), "+v"(o[3]));
;         auto rr = __builtin_amdgcn_permlane32_swap(__float_as_uint(l_reg), __float_as_uint(l_reg), false, false); l_reg = __uint_as_float(rr[0]) + __uint_as_float(rr[1]); }
	v_mfma_scale_f32_32x32x64_f8f6f4 v[16:31], v[80:87], v[72:79], v[16:31], v189, v189 op_sel_hi:[0,0,0] cbsz:1
	ds_read_b128 v[88:91], v130 offset:5120
	ds_read_b128 v[92:95], v130 offset:5136
	v_exp_f32_e32 v65, v113
	v_exp_f32_e32 v66, v114
	v_exp_f32_e32 v67, v115
	v_exp_f32_e32 v68, v116
	v_exp_f32_e32 v69, v117
	v_exp_f32_e32 v70, v118
	v_exp_f32_e32 v71, v119
	ds_read_b128 v[116:119], v130 offset:7696
	ds_read_b128 v[112:115], v130 offset:7680
	v_exp_f32_e32 v72, v120
	v_exp_f32_e32 v73, v121
	v_exp_f32_e32 v74, v122
	v_exp_f32_e32 v75, v123
	v_exp_f32_e32 v76, v124
	v_exp_f32_e32 v77, v125
	v_exp_f32_e32 v78, v126
	v_exp_f32_e32 v79, v127
	s_waitcnt lgkmcnt(0)
	s_waitcnt lgkmcnt(2)
	v_mfma_scale_f32_32x32x64_f8f6f4 v[32:47], v[80:87], v[88:95], v[32:47], v189, v189 op_sel_hi:[0,0,0] cbsz:1
	s_waitcnt lgkmcnt(0)
	v_mfma_scale_f32_32x32x64_f8f6f4 v[48:63], v[80:87], v[112:119], v[48:63], v189, v189 op_sel_hi:[0,0,0] cbsz:1
	v_exp_f32_e32 v85, v96
	v_add_f32_e32 v80, 0, v64
	v_add_f32_e32 v80, v65, v80
	v_add_f32_e32 v80, v66, v80
	v_add_f32_e32 v80, v67, v80
	v_add_f32_e32 v80, v68, v80
	v_add_f32_e32 v80, v69, v80
	v_add_f32_e32 v80, v70, v80
	v_add_f32_e32 v80, v71, v80
	v_add_f32_e32 v80, v72, v80
	v_add_f32_e32 v80, v73, v80
	v_add_f32_e32 v80, v74, v80
	v_add_f32_e32 v80, v75, v80
	v_add_f32_e32 v80, v76, v80
	v_exp_f32_e32 v86, v97
	v_add_f32_e32 v80, v77, v80
	v_exp_f32_e32 v88, v98
	v_add_f32_e32 v80, v78, v80
	v_exp_f32_e32 v89, v99
	v_add_f32_e32 v80, v79, v80
	v_exp_f32_e32 v87, v100
	v_add_f32_e32 v80, v85, v80
	v_exp_f32_e32 v90, v101
	v_add_f32_e32 v80, v86, v80
	v_exp_f32_e32 v91, v102
	v_add_f32_e32 v80, v88, v80
	v_exp_f32_e32 v92, v103
	v_add_f32_e32 v80, v89, v80
	v_exp_f32_e32 v93, v104
	v_add_f32_e32 v80, v87, v80
	v_exp_f32_e32 v94, v105
	v_add_f32_e32 v80, v90, v80
	v_exp_f32_e32 v95, v106
	v_add_f32_e32 v80, v91, v80
	v_exp_f32_e32 v96, v107
	v_add_f32_e32 v80, v92, v80
	v_exp_f32_e32 v97, v108
	v_add_f32_e32 v80, v93, v80
	v_exp_f32_e32 v98, v109
	v_add_f32_e32 v80, v94, v80
	v_add_f32_e32 v80, v95, v80
	v_exp_f32_e32 v99, v110
	v_add_f32_e32 v80, v96, v80
	v_mov_b32_e32 v84, v179
	v_exp_f32_e32 v100, v111
	v_add_f32_e32 v80, v97, v80
	v_cvt_pk_bf8_f32 v84, v85, v86
	v_mov_b32_e32 v85, v179
	v_add_f32_e32 v101, v98, v80
	v_mov_b32_e32 v80, v179
	v_mov_b32_e32 v81, v179
	v_mov_b32_e32 v82, v179
	v_mov_b32_e32 v83, v179
	v_cvt_pk_bf8_f32 v85, v87, v90
	v_mov_b32_e32 v86, v179
	v_mov_b32_e32 v87, v179
	v_cvt_pk_bf8_f32 v80, v64, v65
	v_cvt_pk_bf8_f32 v81, v68, v69
	v_cvt_pk_bf8_f32 v82, v72, v73
	v_cvt_pk_bf8_f32 v83, v76, v77
	v_cvt_pk_bf8_f32 v86, v93, v94
	v_cvt_pk_bf8_f32 v87, v97, v98
	v_add_f32_e32 v64, v99, v101
	v_add_f32_e32 v64, v100, v64
	v_add_f32_e32 v64, v129, v64
	v_cvt_pk_bf8_f32 v80, v66, v67 op_sel:[0,0,1]
	v_cvt_pk_bf8_f32 v81, v70, v71 op_sel:[0,0,1]
	v_cvt_pk_bf8_f32 v82, v74, v75 op_sel:[0,0,1]
	v_cvt_pk_bf8_f32 v83, v78, v79 op_sel:[0,0,1]
	v_cvt_pk_bf8_f32 v84, v88, v89 op_sel:[0,0,1]
	v_cvt_pk_bf8_f32 v85, v91, v92 op_sel:[0,0,1]
	v_cvt_pk_bf8_f32 v86, v95, v96 op_sel:[0,0,1]
	v_cvt_pk_bf8_f32 v87, v99, v100 op_sel:[0,0,1]
	v_add3_u32 v65, s49, v197, v193
	ds_read_b128 v[66:69], v65
	ds_read_b128 v[70:73], v65 offset:16
	ds_read_b128 v[92:95], v65 offset:2576
	ds_read_b128 v[88:91], v65 offset:2560
	s_waitcnt lgkmcnt(0)
	v_cmp_gt_u32_e32 vcc, 32, v196
	s_waitcnt lgkmcnt(2)
	v_mfma_scale_f32_32x32x64_f8f6f4 v[0:15], v[80:87], v[66:73], v[0:15], v189, v189 op_sel_hi:[0,0,0] cbsz:1
	s_waitcnt lgkmcnt(0)
	v_mfma_scale_f32_32x32x64_f8f6f4 v[16:31], v[80:87], v[88:95], v[16:31], v189, v189 op_sel_hi:[0,0,0] cbsz:1
	ds_read_b128 v[66:69], v65 offset:5120
	ds_read_b128 v[70:73], v65 offset:5136
	ds_read_b128 v[92:95], v65 offset:7696
	ds_read_b128 v[88:91], v65 offset:7680
	s_waitcnt lgkmcnt(0)
	v_mov_b32_e32 v65, v64
	s_waitcnt lgkmcnt(2)
	v_mfma_scale_f32_32x32x64_f8f6f4 v[32:47], v[80:87], v[66:73], v[32:47], v189, v189 op_sel_hi:[0,0,0] cbsz:1
	s_waitcnt lgkmcnt(0)
	v_mfma_scale_f32_32x32x64_f8f6f4 v[48:63], v[80:87], v[88:95], v[48:63], v189, v189 op_sel_hi:[0,0,0] cbsz:1
	v_permlane32_swap_b32_e32 v64, v65
	s_nop 15
 s_nop 15
 s_nop 15
 s_nop 15
 s_nop 15
	s_and_saveexec_b64 s[44:45], vcc
	s_cbranch_execz .LBB0_1021
	v_add_f32_e32 v64, v64, v65
	v_lshl_add_u32 v65, v192, 2, v128
	ds_write_b32 v65, v64
	s_branch .LBB0_1021
